# scan odd-chunk convert: counted vmcnt waits relaxed by one (the previous chunk's bonus store no longer forces a full wait for the just-issued y store)
# baseline (speedup 1.0000x reference)
; DI void scan_item(const Params& p, int b, int h, int half, char* smem, unsigned* pgen, unsigned kp) {
;     ...
;   auto convert = [&](const ScanRaw& R) {
;     const float4 mu_r = *(const float4*)(CT + lc);
;     const float4 mu_v = *(const float4*)(CT + 64 + lc);
;     const float4 rk = *(const float4*)(CT + 128 + lc);
;     pw = R.w; pk = R.k; pkk = R.kk; pa = R.a;
;     float c0, p0;
;     c0 = lo_bf(R.rc.x); p0 = lo_bf(R.rp.x); pr.x = c0 + (p0 - c0) * mu_r.x;
;     c0 = hi_bf(R.rc.x); p0 = hi_bf(R.rp.x); pr.y = c0 + (p0 - c0) * mu_r.y;
;     c0 = lo_bf(R.rc.y); p0 = lo_bf(R.rp.y); pr.z = c0 + (p0 - c0) * mu_r.z;
;     c0 = hi_bf(R.rc.y); p0 = hi_bf(R.rp.y); pr.w = c0 + (p0 - c0) * mu_r.w;
;     c0 = lo_bf(R.vc.x); p0 = lo_bf(R.vp.x); pv.x = c0 + (p0 - c0) * mu_v.x;
;     c0 = hi_bf(R.vc.x); p0 = hi_bf(R.vp.x); pv.y = c0 + (p0 - c0) * mu_v.y;
;     c0 = lo_bf(R.vc.y); p0 = lo_bf(R.vp.y); pv.z = c0 + (p0 - c0) * mu_v.z;
;     c0 = hi_bf(R.vc.y); p0 = hi_bf(R.vp.y); pv.w = c0 + (p0 - c0) * mu_v.w;
;     pbon = row16_sum(pr.x * pk.x * rk.x + pr.y * pk.y * rk.y + pr.z * pk.z * rk.z + pr.w * pk.w * rk.w);
;   };
;   auto override_t0 = [&]() {
;     const float* t0 = (const float*)(p.ws + OFF_T0) + (size_t)b * 17 * 64;
;     const float4 r0 = *(const float4*)(t0 + h * 64 + lc);
;     const float4 k0 = *(const float4*)(t0 + (8 + h) * 64 + lc);
;     float av[4] = {p.a0[hc], p.a0[hc + 1], p.a0[hc + 2], p.a0[hc + 3]};
;     for (int j = 0; j < 64; ++j) {
;       const float xj = t0[16 * 64 + j];
;       const float4 a2r = *(const float4*)(p.a2 + (size_t)j * 512 + hc);
;       av[0] += xj * a2r.x; av[1] += xj * a2r.y; av[2] += xj * a2r.z; av[3] += xj * a2r.w;
;     }
;     const float4 kkw = *(const float4*)(p.k_k + hc);
;     const float4 kaw = *(const float4*)(p.k_a + hc);
;     const float4 rk = *(const float4*)(CT + 128 + lc);
;     const float kv[4] = {k0.x, k0.y, k0.z, k0.w}, kkc[4] = {kkw.x, kkw.y, kkw.z, kkw.w}, kac[4] = {kaw.x, kaw.y, kaw.z, kaw.w};
;     float kkv[4], kpv[4], aa[4], ssq = 0.f;
; #pragma unroll
;     for (int e = 0; e < 4; ++e) { aa[e] = sigmoidf_(av[e]); kkv[e] = kv[e] * kkc[e]; ssq += kkv[e] * kkv[e]; kpv[e] = kv[e] * (1.f + (aa[e] - 1.f) * kac[e]); }
;     ssq = row16_sum(ssq);
;     const float inv = rsqrtf(fmaxf(ssq, 1e-24f));
;     pr = r0;
;     pk = make_float4(kpv[0], kpv[1], kpv[2], kpv[3]);
.LBB0_707:
	s_or_b64 exec, exec, s[18:19]
	s_barrier
	ds_read_b128 v[34:37], v193 offset:29440
	ds_read_b128 v[38:41], v193 offset:28928
	s_waitcnt vmcnt(5)
	v_cvt_f32_f16_sdwa v43, v140 dst_sel:DWORD dst_unused:UNUSED_PAD src0_sel:WORD_1
	v_cvt_f32_f16_e32 v42, v140
	s_waitcnt vmcnt(3)
	v_cvt_f32_f16_sdwa v45, v146 dst_sel:DWORD dst_unused:UNUSED_PAD src0_sel:WORD_1
	v_cvt_f32_f16_e32 v44, v146
	v_pk_add_f32 v[44:45], v[44:45], v[42:43] neg_lo:[0,1] neg_hi:[0,1]
	s_waitcnt lgkmcnt(0)
	v_pk_fma_f32 v[38:39], v[44:45], v[38:39], v[42:43]
	v_cvt_f32_f16_sdwa v43, v141 dst_sel:DWORD dst_unused:UNUSED_PAD src0_sel:WORD_1
	v_cvt_f32_f16_e32 v42, v141
	v_cvt_f32_f16_sdwa v45, v147 dst_sel:DWORD dst_unused:UNUSED_PAD src0_sel:WORD_1
	v_cvt_f32_f16_e32 v44, v147
	v_pk_add_f32 v[44:45], v[44:45], v[42:43] neg_lo:[0,1] neg_hi:[0,1]
	s_nop 0
	v_pk_fma_f32 v[40:41], v[44:45], v[40:41], v[42:43]
	v_mul_f32_e32 v43, v19, v39
	v_mul_f32_e32 v42, v18, v38
	v_mul_f32_e32 v35, v43, v35
	v_fmac_f32_e32 v35, v42, v34
	v_mul_f32_e32 v34, v20, v40
	v_fmac_f32_e32 v35, v34, v36
	v_mul_f32_e32 v34, v21, v41
	ds_write_b128 v195, v[38:41]
	ds_write_b128 v195, v[14:17] offset:4096
	ds_write_b128 v195, v[18:21] offset:8192
	v_fmac_f32_e32 v35, v34, v37
	ds_read_b128 v[36:39], v193 offset:29184
	v_cvt_f32_f16_sdwa v41, v144 dst_sel:DWORD dst_unused:UNUSED_PAD src0_sel:WORD_1
	v_cvt_f32_f16_e32 v40, v144
	s_waitcnt vmcnt(2)
	v_cvt_f32_f16_sdwa v43, v148 dst_sel:DWORD dst_unused:UNUSED_PAD src0_sel:WORD_1
	v_cvt_f32_f16_e32 v42, v148
	v_add_f32_dpp v34, v35, v35 row_ror:8 row_mask:0xf bank_mask:0xf bound_ctrl:1
	v_mov_b32_e32 v35, 0
	v_pk_add_f32 v[42:43], v[42:43], v[40:41] neg_lo:[0,1] neg_hi:[0,1]
	s_waitcnt lgkmcnt(0)
	v_pk_fma_f32 v[36:37], v[42:43], v[36:37], v[40:41]
	v_cvt_f32_f16_sdwa v41, v145 dst_sel:DWORD dst_unused:UNUSED_PAD src0_sel:WORD_1
	v_cvt_f32_f16_e32 v40, v145
	v_cvt_f32_f16_sdwa v43, v149 dst_sel:DWORD dst_unused:UNUSED_PAD src0_sel:WORD_1
	v_cvt_f32_f16_e32 v42, v149
	v_add_f32_dpp v34, v34, v34 row_ror:4 row_mask:0xf bank_mask:0xf bound_ctrl:1
	v_pk_add_f32 v[42:43], v[42:43], v[40:41] neg_lo:[0,1] neg_hi:[0,1]
	s_nop 0
	v_pk_fma_f32 v[38:39], v[42:43], v[38:39], v[40:41]
	v_add_f32_dpp v34, v34, v34 row_ror:2 row_mask:0xf bank_mask:0xf bound_ctrl:1
	ds_write_b128 v195, v[36:39] offset:12288
	v_xor_b32_e32 v39, 0x80000000, v25
	v_xor_b32_e32 v38, 0x80000000, v24
	v_xor_b32_e32 v37, 0x80000000, v23
	v_xor_b32_e32 v36, 0x80000000, v22
	v_mov_b32_dpp v35, v34 row_ror:1 row_mask:0xf bank_mask:0xf
	ds_write_b128 v195, v[36:39] offset:16384
	v_pk_mul_f32 v[38:39], v[24:25], v[32:33]
	v_pk_mul_f32 v[36:37], v[22:23], v[30:31]
	ds_write_b128 v195, v[36:39] offset:20480
	s_mov_b64 s[18:19], exec
	v_readlane_b32 s26, v252, 36
	v_readlane_b32 s27, v252, 37
	s_and_b64 s[26:27], s[18:19], s[26:27]
	s_mov_b64 exec, s[26:27]
	v_add_f32_e32 v34, v34, v35
	ds_write_b32 v171, v34 offset:28672
	s_or_b64 exec, exec, s[18:19]
	s_andn2_b64 vcc, exec, s[4:5]
	s_waitcnt lgkmcnt(0)
	s_barrier
	s_cbranch_vccnz .LBB0_711
	v_add_u32_e32 v0, 48, v0
	v_lshl_add_u64 v[34:35], s[6:7], 0, v[0:1]
	v_alignbit_b32 v0, v35, v34, 12
	v_mov_b64_e32 v[30:31], s[94:95]
	s_mov_b32 s18, 0x2100000
	v_mad_u64_u32 v[30:31], s[4:5], v0, s18, v[30:31]
	v_mov_b32_e32 v0, v31
	v_lshrrev_b32_e32 v31, 12, v35
	v_lshlrev_b64 v[36:37], 11, v[34:35]
	v_mad_u64_u32 v[32:33], s[4:5], v31, s18, v[0:1]
	v_mov_b32_e32 v31, v32
	v_and_b32_e32 v0, 0x7ff800, v36
	v_lshl_add_u64 v[30:31], v[30:31], 0, v[0:1]
	v_and_b32_e32 v32, 0xff800000, v36
	v_mov_b32_e32 v33, v37
	v_lshl_add_u64 v[30:31], v[108:109], 2, v[30:31]
	s_mov_b32 s4, 0x8381000
	v_lshl_add_u64 v[32:33], s[58:59], 0, v[32:33]
	v_lshl_add_u64 v[14:15], v[118:119], 0, v[36:37]
	v_lshl_add_u64 v[18:19], v[120:121], 0, v[36:37]
	v_lshl_add_u64 v[22:23], v[122:123], 0, v[36:37]
	v_add_co_u32_e32 v30, vcc, s4, v30
	v_mad_u64_u32 v[32:33], s[4:5], v34, s67, v[32:33]
	v_lshl_add_u64 v[36:37], v[36:37], 0, s[82:83]
	v_mad_i32_i24 v33, v35, s67, v33
	v_and_b32_e32 v36, 0xff800000, v36
	v_addc_co_u32_e32 v31, vcc, 0, v31, vcc
	v_lshl_add_u64 v[38:39], v[32:33], 0, v[110:111]
	v_lshl_add_u64 v[36:37], s[58:59], 0, v[36:37]
	global_load_dwordx4 v[14:17], v[14:15], off
	s_nop 0
	global_load_dwordx4 v[18:21], v[18:19], off
	s_nop 0
	global_load_dwordx4 v[22:25], v[22:23], off
	s_nop 0
	global_load_dwordx4 v[30:33], v[30:31], off offset:1024
	s_nop 0
	global_load_dwordx2 v[140:141], v[38:39], off offset:2560
	v_add_co_u32_e32 v38, vcc, s15, v38
	v_mad_u64_u32 v[36:37], s[4:5], v34, s67, v[36:37]
	s_nop 0
	v_addc_co_u32_e32 v39, vcc, 0, v39, vcc
	v_mad_i32_i24 v37, v35, s67, v37
	v_lshl_add_u64 v[34:35], v[36:37], 0, v[110:111]
	global_load_dwordx2 v[144:145], v[38:39], off offset:512
	global_load_dwordx2 v[146:147], v[34:35], off offset:-3840
	global_load_dwordx2 v[148:149], v[34:35], off offset:-1792
